# sparse inner loop software-pipelined across key sub-tiles (QK(k) then PV(k-1) with softmax(k) VALU between the PV MFMAs; second P buffer v242-249); v75 otherwise
# speedup vs baseline: 1.0064x; 1.0005x over previous
.LBB0_839:
	s_waitcnt lgkmcnt(14)
	v_sub_u32_e32 v0, s66, v3
	v_lshlrev_b32_e32 v0, 8, v0
	v_add_u32_e32 v0, s10, v0
	v_cmp_ge_i32_e32 vcc, v0, v2
	s_cbranch_vccnz .LBB0_823
	v_mov_b32_e32 v151, 0
	s_mov_b32 s8, 0
	v_mov_b32_e32 v0, 0
	v_mov_b32_e32 v1, v151
	v_mov_b32_e32 v2, v151
	v_mov_b32_e32 v3, v151
	v_mov_b32_e32 v4, v151
	v_mov_b32_e32 v5, v151
	v_mov_b32_e32 v6, v151
	v_mov_b32_e32 v7, v151
	v_mov_b32_e32 v8, v151
	v_mov_b32_e32 v9, v151
	v_mov_b32_e32 v10, v151
	v_mov_b32_e32 v11, v151
	v_mov_b32_e32 v12, v151
	v_mov_b32_e32 v13, v151
	v_mov_b32_e32 v14, v151
	v_mov_b32_e32 v15, v151
	v_mov_b32_e32 v16, 0
	v_mov_b32_e32 v17, v151
	v_mov_b32_e32 v18, v151
	v_mov_b32_e32 v19, v151
	v_mov_b32_e32 v20, v151
	v_mov_b32_e32 v21, v151
	v_mov_b32_e32 v22, v151
	v_mov_b32_e32 v23, v151
	v_mov_b32_e32 v24, v151
	v_mov_b32_e32 v25, v151
	v_mov_b32_e32 v26, v151
	v_mov_b32_e32 v27, v151
	v_mov_b32_e32 v28, v151
	v_mov_b32_e32 v29, v151
	v_mov_b32_e32 v30, v151
	v_mov_b32_e32 v31, v151
	v_mov_b32_e32 v32, 0
	v_mov_b32_e32 v33, v151
	v_mov_b32_e32 v34, v151
	v_mov_b32_e32 v35, v151
	v_mov_b32_e32 v36, v151
	v_mov_b32_e32 v37, v151
	v_mov_b32_e32 v38, v151
	v_mov_b32_e32 v39, v151
	v_mov_b32_e32 v40, v151
	v_mov_b32_e32 v41, v151
	v_mov_b32_e32 v42, v151
	v_mov_b32_e32 v43, v151
	v_mov_b32_e32 v44, v151
	v_mov_b32_e32 v45, v151
	v_mov_b32_e32 v46, v151
	v_mov_b32_e32 v47, v151
	v_mov_b32_e32 v48, 0
	v_mov_b32_e32 v49, v151
	v_mov_b32_e32 v50, v151
	v_mov_b32_e32 v51, v151
	v_mov_b32_e32 v52, v151
	v_mov_b32_e32 v53, v151
	v_mov_b32_e32 v54, v151
	v_mov_b32_e32 v55, v151
	v_mov_b32_e32 v56, v151
	v_mov_b32_e32 v57, v151
	v_mov_b32_e32 v58, v151
	v_mov_b32_e32 v59, v151
	v_mov_b32_e32 v60, v151
	v_mov_b32_e32 v61, v151
	v_mov_b32_e32 v62, v151
	v_mov_b32_e32 v63, v151
	v_mov_b32_e32 v155, v200
	v_mov_b32_e32 v159, v199
	v_mov_b32_e32 v163, v198
	v_mov_b32_e32 v167, v197
	v_mov_b32_e32 v171, v196
	v_mov_b32_e32 v175, v195
	v_mov_b32_e32 v176, v194
	v_mov_b32_e32 v185, v193
	v_add_u32_e32 v241, 0x10000, v192
	ds_read_b128 v[224:227], v155
	ds_read_b128 v[228:231], v159
	ds_read_b128 v[232:235], v163
	ds_read_b128 v[236:239], v167
	s_waitcnt lgkmcnt(3)
	v_mfma_f32_32x32x16_bf16 v[64:79], v[224:227], v[112:115], 0
	ds_read_b128 v[224:227], v171
	s_waitcnt lgkmcnt(3)
	v_mfma_f32_32x32x16_bf16 v[64:79], v[228:231], v[116:119], v[64:79]
	ds_read_b128 v[228:231], v175
	s_waitcnt lgkmcnt(3)
	v_mfma_f32_32x32x16_bf16 v[64:79], v[232:235], v[120:123], v[64:79]
	ds_read_b128 v[232:235], v176
	s_waitcnt lgkmcnt(3)
	v_mfma_f32_32x32x16_bf16 v[64:79], v[236:239], v[124:127], v[64:79]
	ds_read_b128 v[236:239], v185
	s_waitcnt lgkmcnt(3)
	v_mfma_f32_32x32x16_bf16 v[64:79], v[224:227], v[128:131], v[64:79]
	s_waitcnt lgkmcnt(2)
	v_mfma_f32_32x32x16_bf16 v[64:79], v[228:231], v[132:135], v[64:79]
	s_waitcnt lgkmcnt(1)
	v_mfma_f32_32x32x16_bf16 v[64:79], v[232:235], v[136:139], v[64:79]
	s_waitcnt lgkmcnt(0)
	v_mfma_f32_32x32x16_bf16 v[64:79], v[236:239], v[140:143], v[64:79]
	v_add_u32_e32 v155, 0x2000, v155
	v_add_u32_e32 v159, 0x2000, v159
	v_add_u32_e32 v163, 0x2000, v163
	v_add_u32_e32 v167, 0x2000, v167
	v_add_u32_e32 v171, 0x2000, v171
	v_add_u32_e32 v175, 0x2000, v175
	v_add_u32_e32 v176, 0x2000, v176
	v_add_u32_e32 v185, 0x2000, v185
	s_nop 3
	ds_read_b128 v[224:227], v155
	ds_read_b128 v[228:231], v159
	ds_read_b128 v[232:235], v163
	ds_read_b128 v[236:239], v167
	v_exp_f32_e32 v64, v64
	v_exp_f32_e32 v65, v65
	v_exp_f32_e32 v66, v66
	v_exp_f32_e32 v67, v67
	v_exp_f32_e32 v68, v68
	v_exp_f32_e32 v69, v69
	v_exp_f32_e32 v70, v70
	v_exp_f32_e32 v71, v71
	v_exp_f32_e32 v72, v72
	v_exp_f32_e32 v73, v73
	v_exp_f32_e32 v74, v74
	v_exp_f32_e32 v75, v75
	v_exp_f32_e32 v76, v76
	v_exp_f32_e32 v77, v77
	v_exp_f32_e32 v78, v78
	v_exp_f32_e32 v79, v79
	v_cvt_pk_bf16_f32 v242, v64, v65
	v_cvt_pk_bf16_f32 v243, v66, v67
	v_cvt_pk_bf16_f32 v244, v68, v69
	v_cvt_pk_bf16_f32 v245, v70, v71
	v_cvt_pk_bf16_f32 v246, v72, v73
	v_cvt_pk_bf16_f32 v247, v74, v75
	v_cvt_pk_bf16_f32 v248, v76, v77
	v_cvt_pk_bf16_f32 v249, v78, v79
	v_add_f32_e32 v240, 0, v64
	v_add_f32_e32 v240, v65, v240
	v_add_f32_e32 v240, v66, v240
	v_add_f32_e32 v240, v67, v240
	v_add_f32_e32 v240, v68, v240
	v_add_f32_e32 v240, v69, v240
	v_add_f32_e32 v240, v70, v240
	v_add_f32_e32 v240, v71, v240
	v_add_f32_e32 v240, v72, v240
	v_add_f32_e32 v240, v73, v240
	v_add_f32_e32 v240, v74, v240
	v_add_f32_e32 v240, v75, v240
	v_add_f32_e32 v240, v76, v240
	v_add_f32_e32 v240, v77, v240
	v_add_f32_e32 v240, v78, v240
	v_add_f32_e32 v240, v79, v240
	v_add_f32_e32 v151, v151, v240
	s_movk_i32 s8, 0x2000
.LBB0_841:
	s_waitcnt lgkmcnt(3)
	v_mfma_f32_32x32x16_bf16 v[64:79], v[224:227], v[112:115], 0
	ds_read_b128 v[224:227], v171
	s_waitcnt lgkmcnt(3)
	v_mfma_f32_32x32x16_bf16 v[64:79], v[228:231], v[116:119], v[64:79]
	ds_read_b128 v[228:231], v175
	s_waitcnt lgkmcnt(3)
	v_mfma_f32_32x32x16_bf16 v[64:79], v[232:235], v[120:123], v[64:79]
	ds_read_b128 v[232:235], v176
	s_waitcnt lgkmcnt(3)
	v_mfma_f32_32x32x16_bf16 v[64:79], v[236:239], v[124:127], v[64:79]
	ds_read_b128 v[236:239], v185
	ds_read_b64_tr_b16 v[208:209], v241
	ds_read_b64_tr_b16 v[210:211], v241 offset:2048
	s_waitcnt lgkmcnt(5)
	v_mfma_f32_32x32x16_bf16 v[64:79], v[224:227], v[128:131], v[64:79]
	ds_read_b64_tr_b16 v[212:213], v241 offset:256
	ds_read_b64_tr_b16 v[214:215], v241 offset:2304
	s_waitcnt lgkmcnt(6)
	v_mfma_f32_32x32x16_bf16 v[64:79], v[228:231], v[132:135], v[64:79]
	ds_read_b64_tr_b16 v[216:217], v241 offset:512
	ds_read_b64_tr_b16 v[218:219], v241 offset:2560
	s_waitcnt lgkmcnt(7)
	v_mfma_f32_32x32x16_bf16 v[64:79], v[232:235], v[136:139], v[64:79]
	ds_read_b64_tr_b16 v[220:221], v241 offset:768
	ds_read_b64_tr_b16 v[222:223], v241 offset:2816
	s_waitcnt lgkmcnt(8)
	v_mfma_f32_32x32x16_bf16 v[64:79], v[236:239], v[140:143], v[64:79]
	s_waitcnt lgkmcnt(6)
	v_mfma_f32_32x32x16_bf16 v[48:63], v[208:211], v[242:245], v[48:63]
	ds_read_b64_tr_b16 v[208:209], v241 offset:4096
	ds_read_b64_tr_b16 v[210:211], v241 offset:6144
	v_add_u32_e32 v155, 0x2000, v155
	v_add_u32_e32 v159, 0x2000, v159
	v_add_u32_e32 v163, 0x2000, v163
	v_add_u32_e32 v167, 0x2000, v167
	v_add_u32_e32 v171, 0x2000, v171
	v_add_u32_e32 v175, 0x2000, v175
	v_add_u32_e32 v176, 0x2000, v176
	v_add_u32_e32 v185, 0x2000, v185
	s_waitcnt lgkmcnt(6)
	v_mfma_f32_32x32x16_bf16 v[32:47], v[212:215], v[242:245], v[32:47]
	ds_read_b64_tr_b16 v[212:213], v241 offset:4352
	ds_read_b64_tr_b16 v[214:215], v241 offset:6400
	s_nop 1
	v_exp_f32_e32 v64, v64
	v_exp_f32_e32 v65, v65
	s_waitcnt lgkmcnt(6)
	v_mfma_f32_32x32x16_bf16 v[16:31], v[216:219], v[242:245], v[16:31]
	ds_read_b64_tr_b16 v[216:217], v241 offset:4608
	ds_read_b64_tr_b16 v[218:219], v241 offset:6656
	v_exp_f32_e32 v66, v66
	v_exp_f32_e32 v67, v67
	s_waitcnt lgkmcnt(6)
	v_mfma_f32_32x32x16_bf16 v[0:15], v[220:223], v[242:245], v[0:15]
	ds_read_b64_tr_b16 v[220:221], v241 offset:4864
	ds_read_b64_tr_b16 v[222:223], v241 offset:6912
	v_exp_f32_e32 v68, v68
	v_exp_f32_e32 v69, v69
	s_waitcnt lgkmcnt(6)
	v_mfma_f32_32x32x16_bf16 v[48:63], v[208:211], v[246:249], v[48:63]
	ds_read_b128 v[224:227], v155
	v_exp_f32_e32 v70, v70
	v_exp_f32_e32 v71, v71
	s_waitcnt lgkmcnt(5)
	v_mfma_f32_32x32x16_bf16 v[32:47], v[212:215], v[246:249], v[32:47]
	ds_read_b128 v[228:231], v159
	v_exp_f32_e32 v72, v72
	v_exp_f32_e32 v73, v73
	s_waitcnt lgkmcnt(4)
	v_mfma_f32_32x32x16_bf16 v[16:31], v[216:219], v[246:249], v[16:31]
	ds_read_b128 v[232:235], v163
	v_exp_f32_e32 v74, v74
	v_exp_f32_e32 v75, v75
	s_waitcnt lgkmcnt(3)
	v_mfma_f32_32x32x16_bf16 v[0:15], v[220:223], v[246:249], v[0:15]
	ds_read_b128 v[236:239], v167
	v_exp_f32_e32 v76, v76
	v_exp_f32_e32 v77, v77
	v_exp_f32_e32 v78, v78
	v_exp_f32_e32 v79, v79
	v_cvt_pk_bf16_f32 v242, v64, v65
	v_cvt_pk_bf16_f32 v243, v66, v67
	v_cvt_pk_bf16_f32 v244, v68, v69
	v_cvt_pk_bf16_f32 v245, v70, v71
	v_cvt_pk_bf16_f32 v246, v72, v73
	v_cvt_pk_bf16_f32 v247, v74, v75
	v_cvt_pk_bf16_f32 v248, v76, v77
	v_cvt_pk_bf16_f32 v249, v78, v79
	v_add_f32_e32 v240, 0, v64
	v_add_f32_e32 v240, v65, v240
	v_add_f32_e32 v240, v66, v240
	v_add_f32_e32 v240, v67, v240
	v_add_f32_e32 v240, v68, v240
	v_add_f32_e32 v240, v69, v240
	v_add_f32_e32 v240, v70, v240
	v_add_f32_e32 v240, v71, v240
	v_add_f32_e32 v240, v72, v240
	v_add_f32_e32 v240, v73, v240
	v_add_f32_e32 v240, v74, v240
	v_add_f32_e32 v240, v75, v240
	v_add_f32_e32 v240, v76, v240
	v_add_f32_e32 v240, v77, v240
	v_add_f32_e32 v240, v78, v240
	v_add_f32_e32 v240, v79, v240
	v_add_f32_e32 v151, v151, v240
	v_add_u32_e32 v241, 0x2000, v241
	s_addk_i32 s8, 0x2000
	s_cmp_lg_u32 s8, 0x10000
	s_cbranch_scc1 .LBB0_841
	ds_read_b64_tr_b16 v[208:209], v241
	ds_read_b64_tr_b16 v[210:211], v241 offset:2048
	ds_read_b64_tr_b16 v[212:213], v241 offset:256
	ds_read_b64_tr_b16 v[214:215], v241 offset:2304
	ds_read_b64_tr_b16 v[216:217], v241 offset:512
	ds_read_b64_tr_b16 v[218:219], v241 offset:2560
	ds_read_b64_tr_b16 v[220:221], v241 offset:768
	ds_read_b64_tr_b16 v[222:223], v241 offset:2816
	s_waitcnt lgkmcnt(6)
	v_mfma_f32_32x32x16_bf16 v[48:63], v[208:211], v[242:245], v[48:63]
	ds_read_b64_tr_b16 v[208:209], v241 offset:4096
	ds_read_b64_tr_b16 v[210:211], v241 offset:6144
	s_waitcnt lgkmcnt(6)
	v_mfma_f32_32x32x16_bf16 v[32:47], v[212:215], v[242:245], v[32:47]
	ds_read_b64_tr_b16 v[212:213], v241 offset:4352
	ds_read_b64_tr_b16 v[214:215], v241 offset:6400
	s_waitcnt lgkmcnt(6)
	v_mfma_f32_32x32x16_bf16 v[16:31], v[216:219], v[242:245], v[16:31]
	ds_read_b64_tr_b16 v[216:217], v241 offset:4608
	ds_read_b64_tr_b16 v[218:219], v241 offset:6656
	s_waitcnt lgkmcnt(6)
	v_mfma_f32_32x32x16_bf16 v[0:15], v[220:223], v[242:245], v[0:15]
	ds_read_b64_tr_b16 v[220:221], v241 offset:4864
	ds_read_b64_tr_b16 v[222:223], v241 offset:6912
	s_waitcnt lgkmcnt(6)
	v_mfma_f32_32x32x16_bf16 v[48:63], v[208:211], v[246:249], v[48:63]
	s_waitcnt lgkmcnt(4)
	v_mfma_f32_32x32x16_bf16 v[32:47], v[212:215], v[246:249], v[32:47]
	s_waitcnt lgkmcnt(2)
	v_mfma_f32_32x32x16_bf16 v[16:31], v[216:219], v[246:249], v[16:31]
	s_waitcnt lgkmcnt(0)
	v_mfma_f32_32x32x16_bf16 v[0:15], v[220:223], v[246:249], v[0:15]
	s_waitcnt lgkmcnt(0)
	ds_bpermute_b32 v66, v191, v151
	v_lshrrev_b32_e32 v65, 2, v207
	v_cmp_ne_u32_e32 vcc, -1, v207
	v_and_b32_e32 v64, 3, v207
	v_lshl_add_u32 v65, s68, 13, v65
	v_mad_u64_u32 v[64:65], s[8:9], v65, 3, v[64:65]
	s_and_b64 s[30:31], vcc, s[4:5]
	s_and_saveexec_b64 s[8:9], s[30:31]
	s_cbranch_execz .LBB0_844
	v_ashrrev_i32_e32 v65, 31, v64
	s_waitcnt lgkmcnt(0)
	v_add_f32_e32 v68, v151, v66
	v_lshl_add_u64 v[66:67], v[64:65], 2, s[36:37]
	global_store_dword v[66:67], v68, off
	s_add_u32 s98, s98, 1
